# nt hint also on the read-once f32 weight loads of layer 1's weight conversions (idle half of L0 gate/up, L1 in-proj tail)
# speedup vs baseline: 1.0180x; 1.0057x over previous
.LBB0_738:
	s_waitcnt vmcnt(0)
	v_cvt_f32_u32_e32 v34, s30
	s_sub_i32 s31, 0, s30
	s_abs_i32 s23, s8
	s_ashr_i32 s22, s8, 31
	v_rcp_iflag_f32_e32 v34, v34
	v_lshlrev_b32_e32 v66, 2, v230
	v_mul_f32_e32 v34, 0x4f7ffffe, v34
	v_cvt_u32_f32_e32 v34, v34
	s_nop 0
	v_readfirstlane_b32 s38, v34
	s_mul_i32 s31, s31, s38
	s_mul_hi_u32 s31, s38, s31
	s_add_i32 s38, s38, s31
	s_mul_hi_u32 s31, s23, s38
	s_mul_i32 s38, s31, s30
	s_sub_i32 s23, s23, s38
	s_add_i32 s39, s31, 1
	s_sub_i32 s38, s23, s30
	s_cmp_ge_u32 s23, s30
	s_cselect_b32 s31, s39, s31
	s_cselect_b32 s23, s38, s23
	s_add_i32 s38, s31, 1
	s_cmp_ge_u32 s23, s30
	s_cselect_b32 s23, s38, s31
	s_xor_b32 s23, s23, s22
	s_sub_i32 s22, s23, s22
	s_mul_i32 s23, s22, s30
	s_sub_i32 s8, s8, s23
	s_lshl_b32 s30, s22, 6
	s_lshl_b32 s22, s8, 5
	s_ashr_i32 s23, s22, 31
	s_lshl_b64 s[22:23], s[22:23], 2
	s_add_u32 s20, s20, s22
	v_or_b32_e32 v42, s30, v199
	s_addc_u32 s21, s21, s23
	s_ashr_i32 s8, s30, 31
	v_lshl_add_u64 v[34:35], s[20:21], 0, v[66:67]
	s_mul_i32 s8, s18, s8
	v_mul_lo_u32 v38, s19, v42
	v_mad_u64_u32 v[36:37], s[20:21], s18, v42, 0
	v_add3_u32 v37, v37, s8, v38
	v_or_b32_e32 v38, 8, v42
	v_mul_lo_u32 v40, s19, v38
	v_mad_u64_u32 v[38:39], s[20:21], s18, v38, 0
	v_lshl_add_u64 v[36:37], v[36:37], 2, v[34:35]
	v_add3_u32 v39, v39, s8, v40
	v_lshl_add_u64 v[38:39], v[38:39], 2, v[34:35]
	global_load_dwordx4 v[62:65], v[36:37], off nt
	global_load_dwordx4 v[58:61], v[38:39], off nt
	v_or_b32_e32 v36, 16, v42
	v_mul_lo_u32 v38, s19, v36
	v_mad_u64_u32 v[36:37], s[20:21], s18, v36, 0
	v_add3_u32 v37, v37, s8, v38
	v_or_b32_e32 v38, 24, v42
	v_mul_lo_u32 v40, s19, v38
	v_mad_u64_u32 v[38:39], s[20:21], s18, v38, 0
	v_lshl_add_u64 v[36:37], v[36:37], 2, v[34:35]
	v_add3_u32 v39, v39, s8, v40
	v_lshl_add_u64 v[38:39], v[38:39], 2, v[34:35]
	global_load_dwordx4 v[54:57], v[36:37], off nt
	global_load_dwordx4 v[46:49], v[38:39], off nt
	v_or_b32_e32 v36, 32, v42
	v_mul_lo_u32 v38, s19, v36
	v_mad_u64_u32 v[36:37], s[20:21], s18, v36, 0
	v_add3_u32 v37, v37, s8, v38
	v_or_b32_e32 v38, 40, v42
	v_mul_lo_u32 v40, s19, v38
	v_mad_u64_u32 v[38:39], s[20:21], s18, v38, 0
	v_add3_u32 v39, v39, s8, v40
	v_lshl_add_u64 v[36:37], v[36:37], 2, v[34:35]
	v_lshl_add_u64 v[38:39], v[38:39], 2, v[34:35]
	global_load_dwordx4 v[50:53], v[36:37], off nt
	s_nop 0
	global_load_dwordx4 v[38:41], v[38:39], off nt
	v_or_b32_e32 v36, 48, v42
	v_mul_lo_u32 v43, s19, v36
	v_mad_u64_u32 v[36:37], s[20:21], s18, v36, 0
	v_or_b32_e32 v42, 56, v42
	v_add3_u32 v37, v37, s8, v43
	v_mul_lo_u32 v44, s19, v42
	v_mad_u64_u32 v[42:43], s[18:19], s18, v42, 0
	v_add3_u32 v43, v43, s8, v44
	v_lshl_add_u64 v[36:37], v[36:37], 2, v[34:35]
	v_lshl_add_u64 v[34:35], v[42:43], 2, v[34:35]
	global_load_dwordx4 v[42:45], v[36:37], off nt
	s_nop 0
	global_load_dwordx4 v[34:37], v[34:35], off nt
	s_xor_b64 s[10:11], s[10:11], -1
	s_andn2_b64 vcc, exec, s[16:17]
	s_cbranch_vccnz .LBB0_722

.LBB0_769:
	v_cvt_f32_u32_e32 v2, s39
	s_sub_i32 s40, 0, s39
	s_abs_i32 s23, s8
	s_ashr_i32 s22, s8, 31
	v_rcp_iflag_f32_e32 v2, v2
	v_lshlrev_b32_e32 v66, 2, v230
	v_mul_f32_e32 v2, 0x4f7ffffe, v2
	v_cvt_u32_f32_e32 v2, v2
	s_nop 0
	v_readfirstlane_b32 s41, v2
	s_mul_i32 s40, s40, s41
	s_mul_hi_u32 s40, s41, s40
	s_add_i32 s41, s41, s40
	s_mul_hi_u32 s40, s23, s41
	s_mul_i32 s41, s40, s39
	s_sub_i32 s23, s23, s41
	s_add_i32 s42, s40, 1
	s_sub_i32 s41, s23, s39
	s_cmp_ge_u32 s23, s39
	s_cselect_b32 s40, s42, s40
	s_cselect_b32 s23, s41, s23
	s_add_i32 s41, s40, 1
	s_cmp_ge_u32 s23, s39
	s_cselect_b32 s23, s41, s40
	s_xor_b32 s23, s23, s22
	s_sub_i32 s22, s23, s22
	s_mul_i32 s23, s22, s39
	s_sub_i32 s8, s8, s23
	s_lshl_b32 s39, s22, 6
	s_lshl_b32 s22, s8, 5
	s_ashr_i32 s23, s22, 31
	s_lshl_b64 s[22:23], s[22:23], 2
	v_or_b32_e32 v30, s39, v199
	s_add_u32 s20, s20, s22
	s_addc_u32 s21, s21, s23
	s_ashr_i32 s8, s39, 31
	v_or_b32_e32 v10, 16, v30
	v_or_b32_e32 v18, 32, v30
	v_lshl_add_u64 v[26:27], s[20:21], 0, v[66:67]
	s_mul_i32 s8, s18, s8
	v_mul_lo_u32 v4, s19, v30
	v_mad_u64_u32 v[2:3], s[20:21], s18, v30, 0
	v_mul_lo_u32 v12, s19, v10
	v_mad_u64_u32 v[10:11], s[20:21], s18, v10, 0
	v_mul_lo_u32 v20, s19, v18
	v_mad_u64_u32 v[18:19], s[20:21], s18, v18, 0
	v_or_b32_e32 v28, 48, v30
	v_add3_u32 v3, v3, s8, v4
	v_or_b32_e32 v4, 8, v30
	v_add3_u32 v11, v11, s8, v12
	v_or_b32_e32 v12, 24, v30
	v_add3_u32 v19, v19, s8, v20
	v_or_b32_e32 v20, 40, v30
	v_mul_lo_u32 v31, s19, v28
	v_mad_u64_u32 v[28:29], s[20:21], s18, v28, 0
	v_or_b32_e32 v30, 56, v30
	v_mul_lo_u32 v6, s19, v4
	v_mad_u64_u32 v[4:5], s[20:21], s18, v4, 0
	v_mul_lo_u32 v14, s19, v12
	v_mad_u64_u32 v[12:13], s[20:21], s18, v12, 0
	v_mul_lo_u32 v22, s19, v20
	v_mad_u64_u32 v[20:21], s[20:21], s18, v20, 0
	v_add3_u32 v29, v29, s8, v31
	v_mul_lo_u32 v32, s19, v30
	v_mad_u64_u32 v[30:31], s[18:19], s18, v30, 0
	v_add3_u32 v5, v5, s8, v6
	v_add3_u32 v13, v13, s8, v14
	v_add3_u32 v21, v21, s8, v22
	v_add3_u32 v31, v31, s8, v32
	v_lshl_add_u64 v[2:3], v[2:3], 2, v[26:27]
	v_lshl_add_u64 v[6:7], v[4:5], 2, v[26:27]
	v_lshl_add_u64 v[10:11], v[10:11], 2, v[26:27]
	v_lshl_add_u64 v[14:15], v[12:13], 2, v[26:27]
	v_lshl_add_u64 v[18:19], v[18:19], 2, v[26:27]
	v_lshl_add_u64 v[22:23], v[20:21], 2, v[26:27]
	v_lshl_add_u64 v[28:29], v[28:29], 2, v[26:27]
	v_lshl_add_u64 v[30:31], v[30:31], 2, v[26:27]
	global_load_dwordx4 v[2:5], v[2:3], off nt
	s_nop 0
	global_load_dwordx4 v[6:9], v[6:7], off nt
	s_nop 0
	global_load_dwordx4 v[10:13], v[10:11], off nt
	s_nop 0
	global_load_dwordx4 v[14:17], v[14:15], off nt
	s_nop 0
	global_load_dwordx4 v[18:21], v[18:19], off nt
	s_nop 0
	global_load_dwordx4 v[22:25], v[22:23], off nt
	s_nop 0
	global_load_dwordx4 v[26:29], v[28:29], off nt
	s_nop 0
	global_load_dwordx4 v[30:33], v[30:31], off nt
	s_cmpk_gt_i32 s29, 0x5ff
	s_mov_b64 s[18:19], -1
	s_cbranch_scc1 .LBB0_752

.LBB0_775:
	s_ashr_i32 s0, s24, 31
	s_lshr_b32 s0, s0, 29
	s_add_i32 s24, s24, s0
	s_lshl_b32 s0, s24, 6
	s_and_b32 s0, s0, 0xfffffe00
	v_or_b32_e32 v2, s0, v0
	s_movk_i32 s0, 0x4000
	v_cmp_gt_i32_e32 vcc, s0, v2
	s_and_saveexec_b64 s[0:1], vcc
	s_cbranch_execz .LBB0_777
	v_and_b32_e32 v3, 0x3ff, v2
	v_mul_u32_u24_e32 v3, 0xc10, v3
	v_readlane_b32 s16, v251, 9
	v_ashrrev_i32_e32 v4, 10, v2
	v_lshlrev_b32_e32 v6, 2, v3
	v_mov_b32_e32 v7, 0
	v_readlane_b32 s18, v251, 11
	v_readlane_b32 s19, v251, 12
	v_ashrrev_i32_e32 v5, 31, v4
	v_ashrrev_i32_e32 v3, 31, v2
	v_lshl_add_u64 v[6:7], s[18:19], 0, v[6:7]
	v_lshl_add_u64 v[4:5], v[4:5], 2, v[6:7]
	v_add_co_u32_e32 v4, vcc, 0x3000, v4
	v_lshl_add_u64 v[2:3], v[2:3], 1, s[34:35]
	s_nop 0
	v_addc_co_u32_e32 v5, vcc, 0, v5, vcc
	global_load_dword v4, v[4:5], off nt
	s_movk_i32 s4, 0x7fff
	v_add_co_u32_e32 v2, vcc, 0x120000, v2
	v_readlane_b32 s17, v251, 10
	s_nop 0
	v_addc_co_u32_e32 v3, vcc, 0, v3, vcc
	v_readlane_b32 s20, v251, 13
	v_readlane_b32 s21, v251, 14
	v_readlane_b32 s22, v251, 15
	v_readlane_b32 s23, v251, 16
	v_readlane_b32 s24, v251, 17
	v_readlane_b32 s25, v251, 18
	v_readlane_b32 s26, v251, 19
	v_readlane_b32 s27, v251, 20
	v_readlane_b32 s28, v251, 21
	v_readlane_b32 s29, v251, 22
	v_readlane_b32 s30, v251, 23
	v_readlane_b32 s31, v251, 24
	s_waitcnt vmcnt(0)
	v_bfe_u32 v5, v4, 16, 1
	v_add3_u32 v4, v4, v5, s4
	global_store_short_d16_hi v[2:3], v4, off

.LBB0_1011:
	s_abs_i32 s11, s10
	v_cvt_f32_u32_e32 v2, s11
	s_sub_i32 s20, 0, s11
	s_abs_i32 s13, s7
	s_xor_b32 s12, s7, s10
	v_rcp_iflag_f32_e32 v2, v2
	s_ashr_i32 s12, s12, 31
	v_lshlrev_b32_e32 v66, 2, v230
	v_mov_b32_e32 v67, 0
	v_mul_f32_e32 v2, 0x4f7ffffe, v2
	v_cvt_u32_f32_e32 v2, v2
	s_mov_b32 s23, 0xffff0000
	v_mov_b32_e32 v76, 0x3db504f3
	v_readfirstlane_b32 s21, v2
	s_mul_i32 s20, s20, s21
	s_mul_hi_u32 s20, s21, s20
	s_add_i32 s21, s21, s20
	s_mul_hi_u32 s20, s13, s21
	s_mul_i32 s21, s20, s11
	s_sub_i32 s13, s13, s21
	s_add_i32 s22, s20, 1
	s_sub_i32 s21, s13, s11
	s_cmp_ge_u32 s13, s11
	s_cselect_b32 s20, s22, s20
	s_cselect_b32 s13, s21, s13
	s_add_i32 s21, s20, 1
	s_cmp_ge_u32 s13, s11
	s_cselect_b32 s11, s21, s20
	s_xor_b32 s11, s11, s12
	s_sub_i32 s11, s11, s12
	s_mul_i32 s10, s11, s10
	s_sub_i32 s7, s7, s10
	s_lshl_b32 s10, s7, 5
	v_lshl_or_b32 v8, s11, 6, v199
	s_ashr_i32 s11, s10, 31
	s_lshl_b64 s[10:11], s[10:11], 2
	s_add_u32 s8, s8, s10
	s_addc_u32 s9, s9, s11
	v_lshl_add_u64 v[2:3], s[8:9], 0, v[66:67]
	v_mad_i64_i32 v[4:5], s[8:9], s6, v8, 0
	v_or_b32_e32 v6, 8, v8
	v_lshl_add_u64 v[4:5], v[4:5], 2, v[2:3]
	v_mad_i64_i32 v[6:7], s[8:9], s6, v6, 0
	v_lshl_add_u64 v[6:7], v[6:7], 2, v[2:3]
	global_load_dwordx4 v[54:57], v[4:5], off nt
	global_load_dwordx4 v[50:53], v[6:7], off nt
	v_or_b32_e32 v4, 16, v8
	v_mad_i64_i32 v[4:5], s[8:9], s6, v4, 0
	v_or_b32_e32 v6, 24, v8
	v_lshl_add_u64 v[4:5], v[4:5], 2, v[2:3]
	v_mad_i64_i32 v[6:7], s[8:9], s6, v6, 0
	v_lshl_add_u64 v[6:7], v[6:7], 2, v[2:3]
	global_load_dwordx4 v[42:45], v[4:5], off nt
	global_load_dwordx4 v[30:33], v[6:7], off nt
	v_or_b32_e32 v4, 32, v8
	v_mad_i64_i32 v[4:5], s[8:9], s6, v4, 0
	v_or_b32_e32 v6, 40, v8
	v_lshl_add_u64 v[4:5], v[4:5], 2, v[2:3]
	v_mad_i64_i32 v[6:7], s[8:9], s6, v6, 0
	v_lshl_add_u64 v[6:7], v[6:7], 2, v[2:3]
	global_load_dwordx4 v[34:37], v[4:5], off nt
	global_load_dwordx4 v[22:25], v[6:7], off nt
	v_or_b32_e32 v4, 48, v8
	v_mad_i64_i32 v[4:5], s[8:9], s6, v4, 0
	v_or_b32_e32 v6, 56, v8
	v_lshl_add_u64 v[4:5], v[4:5], 2, v[2:3]
	v_mad_i64_i32 v[6:7], s[6:7], s6, v6, 0
	v_lshl_add_u64 v[2:3], v[6:7], 2, v[2:3]
	global_load_dwordx4 v[26:29], v[4:5], off nt
	global_load_dwordx4 v[10:13], v[2:3], off nt
	v_readlane_b32 s8, v251, 4
	v_lshlrev_b32_e32 v2, 1, v183
	v_mov_b32_e32 v3, v67
	v_readlane_b32 s9, v251, 5
	v_mul_u32_u24_e32 v4, 0x84, v183
	v_readlane_b32 s6, v251, 8
	v_lshl_add_u64 v[68:69], s[8:9], 0, v[2:3]
	v_readlane_b32 s8, v251, 2
	v_add3_u32 v75, s6, v4, v182
	v_readlane_b32 s9, v251, 3
	s_lshl_b32 s6, s25, 1
	s_mov_b32 s7, 0
	v_lshl_add_u64 v[70:71], s[8:9], 0, v[2:3]
	v_lshl_add_u64 v[72:73], s[86:87], 0, v[2:3]
	s_lshl_b32 s20, s25, 5
	s_add_i32 s21, s6, 0xfffff400
	s_movk_i32 s22, 0x7fff
	s_branch .LBB0_1013

.LBB0_1031:
	v_cvt_f32_ubyte0_e32 v2, s26
	v_rcp_iflag_f32_e32 v2, v2
	s_sub_i32 s28, 0, s26
	s_abs_i32 s27, s6
	s_ashr_i32 s11, s6, 31
	v_mul_f32_e32 v2, 0x4f7ffffe, v2
	v_cvt_u32_f32_e32 v2, v2
	s_nop 0
	v_readfirstlane_b32 s29, v2
	s_mul_i32 s28, s28, s29
	s_mul_hi_u32 s28, s29, s28
	s_add_i32 s29, s29, s28
	s_mul_hi_u32 s28, s27, s29
	s_mul_i32 s29, s28, s26
	s_sub_i32 s27, s27, s29
	s_add_i32 s30, s28, 1
	s_sub_i32 s29, s27, s26
	s_cmp_ge_u32 s27, s26
	s_cselect_b32 s28, s30, s28
	s_cselect_b32 s27, s29, s27
	s_add_i32 s29, s28, 1
	s_cmp_ge_u32 s27, s26
	s_cselect_b32 s27, s29, s28
	s_xor_b32 s27, s27, s11
	s_sub_i32 s11, s27, s11
	s_mul_i32 s26, s11, s26
	s_sub_i32 s6, s6, s26
	s_lshl_b32 s26, s6, 5
	s_ashr_i32 s27, s26, 31
	s_lshl_b64 s[26:27], s[26:27], 2
	s_add_u32 s12, s12, s26
	v_lshl_or_b32 v62, s11, 6, v199
	s_addc_u32 s13, s13, s27
	v_lshl_add_u64 v[58:59], s[12:13], 0, v[66:67]
	v_mad_i64_i32 v[2:3], s[12:13], s10, v62, 0
	v_or_b32_e32 v4, 8, v62
	v_or_b32_e32 v14, 16, v62
	v_or_b32_e32 v16, 24, v62
	v_or_b32_e32 v38, 32, v62
	v_or_b32_e32 v40, 40, v62
	v_or_b32_e32 v60, 48, v62
	v_or_b32_e32 v62, 56, v62
	v_mad_i64_i32 v[4:5], s[12:13], s10, v4, 0
	v_mad_i64_i32 v[14:15], s[12:13], s10, v14, 0
	v_mad_i64_i32 v[16:17], s[12:13], s10, v16, 0
	v_mad_i64_i32 v[38:39], s[12:13], s10, v38, 0
	v_mad_i64_i32 v[40:41], s[12:13], s10, v40, 0
	v_mad_i64_i32 v[60:61], s[12:13], s10, v60, 0
	v_mad_i64_i32 v[62:63], s[10:11], s10, v62, 0
	v_lshl_add_u64 v[2:3], v[2:3], 2, v[58:59]
	v_lshl_add_u64 v[6:7], v[4:5], 2, v[58:59]
	v_lshl_add_u64 v[14:15], v[14:15], 2, v[58:59]
	v_lshl_add_u64 v[18:19], v[16:17], 2, v[58:59]
	v_lshl_add_u64 v[38:39], v[38:39], 2, v[58:59]
	v_lshl_add_u64 v[46:47], v[40:41], 2, v[58:59]
	v_lshl_add_u64 v[60:61], v[60:61], 2, v[58:59]
	v_lshl_add_u64 v[62:63], v[62:63], 2, v[58:59]
	global_load_dwordx4 v[2:5], v[2:3], off nt
	s_nop 0
	global_load_dwordx4 v[6:9], v[6:7], off nt
	s_nop 0
	global_load_dwordx4 v[14:17], v[14:15], off nt
	s_nop 0
	global_load_dwordx4 v[18:21], v[18:19], off nt
	s_nop 0
	global_load_dwordx4 v[38:41], v[38:39], off nt
	s_nop 0
	global_load_dwordx4 v[46:49], v[46:47], off nt
	s_nop 0
	global_load_dwordx4 v[58:61], v[60:61], off nt
	s_nop 0
	global_load_dwordx4 v[62:65], v[62:63], off nt
	s_cmpk_gt_i32 s25, 0x5ff
	s_mov_b64 s[10:11], -1
	s_cbranch_scc1 .LBB0_1019
